# gla_pass2 reloads the per-token cumulative log-decay that gla_pass1 already computed (stored as f32 in the idle MERGED workspace region) instead of recomputing it; staging loads share one wait
# speedup vs baseline: 1.1017x; 1.0108x over previous
; __device__ __forceinline__ float bf_lo(unsigned w) { return __uint_as_float(w << 16); }
; __device__ __forceinline__ float bf_hi(unsigned w) { return __uint_as_float(w & 0xffff0000u); }
; __device__ __forceinline__ float bf2f(bf16_t b) { return __uint_as_float(((unsigned)b) << 16); }
; template <bool OUT>
; __device__ __forceinline__ void gla_chunks(const Params& p, int l, const bf16_t* proj, LAS unsigned char* lds, int seg, int h, int dir, f32x4 (&Sacc)[4], float* outbuf, float& alog) {
;     ...
;         const int t0 = seg * SEGLEN + (dir ? 3 - c : c) * 64;
;         float bq[8], qv[8], kv[8];
;         { u32x4 L0[8], L1[8]; bf16_t kr[8], qr[8];
; #pragma unroll
;           for (int j = 0; j < 8; ++j) { const int i = tb * 8 + j, t = dir ? t0 + 63 - i : t0 + i;
;               const u32x4* lr = (const u32x4*)(proj + (size_t)t * NP + GLR + dir * 16); L0[j] = lr[0]; L1[j] = lr[1];
;               kr[j] = proj[(size_t)t * NP + GK + h * 64 + d]; qr[j] = OUT ? proj[(size_t)t * NP + GQ + h * 64 + d] : (bf16_t)0; }
;           __builtin_amdgcn_sched_barrier(0);
;           float run = 0.f;
; #pragma unroll
;           for (int j = 0; j < 8; ++j) { const u32x4 l0 = L0[j], l1 = L1[j]; float z = bias;
; #pragma unroll
;               for (int e = 0; e < 4; ++e) { z += bf_lo(l0[e]) * w[e * 2] + bf_hi(l0[e]) * w[e * 2 + 1]; z += bf_lo(l1[e]) * w[8 + e * 2] + bf_hi(l1[e]) * w[8 + e * 2 + 1]; }
;               const float ls = fminf(z, 0.f) - __logf(1.0f + __expf(-fabsf(z)));
;               run += ls * (1.0f / 16.0f); bq[j] = run;
;               kv[j] = bf2f(kr[j]);
;               if (OUT) qv[j] = bf2f(qr[j]) * 0.125f; }
;           PART[tb * 64 + d] = run; }
;         { const int pr = tid >> 4, part = tid & 15; const int i0 = 2 * pr, ta = dir ? t0 + 63 - i0 : t0 + i0, tbb = dir ? ta - 1 : ta + 1;
;           const u32x4 a = *(const u32x4*)(proj + (size_t)ta * NP + GV + h * 128 + part * 8), b = *(const u32x4*)(proj + (size_t)tbb * NP + GV + h * 128 + part * 8);
.LBB0_436:
	s_and_b64 s[40:41], s[42:43], exec
	s_cselect_b32 s40, s51, s64
	s_lshl_b32 s52, s40, 6
	s_add_i32 s52, s52, s68
	s_or_b32 s53, s52, 63
	s_sub_i32 s54, s53, s33
	s_add_i32 s55, s52, s33
	s_and_b64 s[40:41], s[42:43], exec
	s_cselect_b32 s40, s55, s54
	s_cselect_b32 s41, 1, -1
	s_lshl_b32 s41, s41, 11
	s_lshl_b32 s54, s40, 11
	s_lshl_b32 s55, s50, 5
	s_add_i32 s54, s54, s55
	s_lshl_b32 s55, s66, 2
	s_add_i32 s54, s54, s55
	s_add_u32 s56, s94, 0x11000000
	s_addc_u32 s57, s95, 0
	v_add_u32_e32 v164, s54, v110
	global_load_dword v156, v164, s[56:57]
	v_add_u32_e32 v165, s41, v164
	global_load_dword v157, v165, s[56:57]
	v_add_u32_e32 v164, s41, v165
	global_load_dword v158, v164, s[56:57]
	v_add_u32_e32 v165, s41, v164
	global_load_dword v159, v165, s[56:57]
	v_add_u32_e32 v164, s41, v165
	global_load_dword v160, v164, s[56:57]
	v_add_u32_e32 v165, s41, v164
	global_load_dword v161, v165, s[56:57]
	v_add_u32_e32 v164, s41, v165
	global_load_dword v162, v164, s[56:57]
	v_add_u32_e32 v165, s41, v164
	global_load_dword v163, v165, s[56:57]
	s_mul_hi_i32 s41, s40, 0x3800
	s_mulk_i32 s40, 0x3800
	s_add_u32 s56, s94, s40
	s_addc_u32 s57, s95, s41
	s_add_u32 s40, s56, s50
	s_addc_u32 s41, s57, 0
	s_add_u32 s54, s40, 0x3600
	s_addc_u32 s55, s41, 0
	s_lshl_b32 s40, s66, 1
	s_add_u32 s54, s56, s40
	s_addc_u32 s55, s57, 0
	s_sub_i32 s41, s53, s77
	s_add_i32 s56, s52, s77
	v_lshl_add_u64 v[16:17], s[54:55], 0, v[188:189]
	s_and_b64 s[54:55], s[42:43], exec
	s_cselect_b32 s41, s56, s41
	s_mul_hi_i32 s54, s41, 0x3800
	s_mulk_i32 s41, 0x3800
	s_add_u32 s41, s94, s41
	s_addc_u32 s58, s95, s54
	s_add_u32 s54, s41, s50
	s_addc_u32 s55, s58, 0
	v_add_co_u32_e32 v16, vcc, s92, v16
	s_add_u32 s56, s54, 0x3600
	s_nop 0
	v_addc_co_u32_e32 v17, vcc, 0, v17, vcc
	s_addc_u32 s57, s55, 0
	global_load_ushort v138, v[16:17], off offset:3072
	global_load_ushort v139, v[16:17], off offset:2560
	s_add_u32 s54, s41, s40
	s_addc_u32 s55, s58, 0
	s_sub_i32 s41, s53, s44
	s_add_i32 s56, s52, s44
	v_lshl_add_u64 v[16:17], s[54:55], 0, v[188:189]
	s_and_b64 s[54:55], s[42:43], exec
	s_cselect_b32 s41, s56, s41
	s_mul_hi_i32 s54, s41, 0x3800
	s_mulk_i32 s41, 0x3800
	s_add_u32 s41, s94, s41
	s_addc_u32 s58, s95, s54
	s_add_u32 s54, s41, s50
	s_addc_u32 s55, s58, 0
	v_add_co_u32_e32 v16, vcc, s92, v16
	s_add_u32 s56, s54, 0x3600
	s_nop 0
	v_addc_co_u32_e32 v17, vcc, 0, v17, vcc
	s_addc_u32 s57, s55, 0
	global_load_ushort v140, v[16:17], off offset:3072
	global_load_ushort v141, v[16:17], off offset:2560
	s_add_u32 s54, s41, s40
	s_addc_u32 s55, s58, 0
	s_sub_i32 s41, s53, s45
	s_add_i32 s56, s52, s45
	v_lshl_add_u64 v[16:17], s[54:55], 0, v[188:189]
	s_and_b64 s[54:55], s[42:43], exec
	s_cselect_b32 s41, s56, s41
	s_mul_hi_i32 s54, s41, 0x3800
	s_mulk_i32 s41, 0x3800
	s_add_u32 s41, s94, s41
	s_addc_u32 s58, s95, s54
	s_add_u32 s54, s41, s50
	s_addc_u32 s55, s58, 0
	v_add_co_u32_e32 v16, vcc, s92, v16
	s_add_u32 s56, s54, 0x3600
	s_nop 0
	v_addc_co_u32_e32 v17, vcc, 0, v17, vcc
	s_addc_u32 s57, s55, 0
	global_load_ushort v142, v[16:17], off offset:3072
	global_load_ushort v143, v[16:17], off offset:2560
	s_add_u32 s54, s41, s40
	s_addc_u32 s55, s58, 0
	s_sub_i32 s41, s53, s46
	s_add_i32 s56, s52, s46
	v_lshl_add_u64 v[16:17], s[54:55], 0, v[188:189]
	s_and_b64 s[54:55], s[42:43], exec
	s_cselect_b32 s41, s56, s41
	s_mul_hi_i32 s54, s41, 0x3800
	s_mulk_i32 s41, 0x3800
	s_add_u32 s41, s94, s41
	s_addc_u32 s58, s95, s54
	s_add_u32 s54, s41, s50
	s_addc_u32 s55, s58, 0
	v_add_co_u32_e32 v16, vcc, s92, v16
	s_add_u32 s56, s54, 0x3600
	s_nop 0
	v_addc_co_u32_e32 v17, vcc, 0, v17, vcc
	s_addc_u32 s57, s55, 0
	global_load_ushort v144, v[16:17], off offset:3072
	global_load_ushort v145, v[16:17], off offset:2560
	s_add_u32 s54, s41, s40
	s_addc_u32 s55, s58, 0
	s_sub_i32 s41, s53, s47
	s_add_i32 s56, s52, s47
	v_lshl_add_u64 v[16:17], s[54:55], 0, v[188:189]
	s_and_b64 s[54:55], s[42:43], exec
	s_cselect_b32 s41, s56, s41
	s_mul_hi_i32 s54, s41, 0x3800
	s_mulk_i32 s41, 0x3800
	s_add_u32 s41, s94, s41
	s_addc_u32 s58, s95, s54
	s_add_u32 s54, s41, s50
	s_addc_u32 s55, s58, 0
	v_add_co_u32_e32 v16, vcc, s92, v16
	s_add_u32 s56, s54, 0x3600
	s_nop 0
	v_addc_co_u32_e32 v17, vcc, 0, v17, vcc
	s_addc_u32 s57, s55, 0
	global_load_ushort v146, v[16:17], off offset:3072
	global_load_ushort v147, v[16:17], off offset:2560
	s_add_u32 s54, s41, s40
	s_addc_u32 s55, s58, 0
	s_sub_i32 s41, s53, s48
	s_add_i32 s56, s52, s48
	v_lshl_add_u64 v[16:17], s[54:55], 0, v[188:189]
	s_and_b64 s[54:55], s[42:43], exec
	s_cselect_b32 s41, s56, s41
	s_mul_hi_i32 s54, s41, 0x3800
	s_mulk_i32 s41, 0x3800
	s_add_u32 s41, s94, s41
	s_addc_u32 s58, s95, s54
	s_add_u32 s54, s41, s50
	s_addc_u32 s55, s58, 0
	v_add_co_u32_e32 v16, vcc, s92, v16
	s_add_u32 s56, s54, 0x3600
	s_nop 0
	v_addc_co_u32_e32 v17, vcc, 0, v17, vcc
	s_addc_u32 s57, s55, 0
	global_load_ushort v148, v[16:17], off offset:3072
	global_load_ushort v149, v[16:17], off offset:2560
	s_add_u32 s54, s41, s40
	s_addc_u32 s55, s58, 0
	s_sub_i32 s41, s53, s49
	s_add_i32 s56, s52, s49
	v_lshl_add_u64 v[16:17], s[54:55], 0, v[188:189]
	s_and_b64 s[54:55], s[42:43], exec
	s_cselect_b32 s41, s56, s41
	s_mul_hi_i32 s54, s41, 0x3800
	s_mulk_i32 s41, 0x3800
	s_add_u32 s41, s94, s41
	s_addc_u32 s58, s95, s54
	s_add_u32 s54, s41, s50
	s_addc_u32 s55, s58, 0
	s_add_u32 s56, s54, 0x3600
	s_addc_u32 s57, s55, 0
	s_add_u32 s40, s41, s40
	v_add_co_u32_e32 v16, vcc, s92, v16
	s_addc_u32 s41, s58, 0
	s_nop 0
	v_addc_co_u32_e32 v17, vcc, 0, v17, vcc
	v_lshl_add_u64 v[152:153], s[40:41], 0, v[188:189]
	s_nop 0
	v_add_co_u32_e32 v154, vcc, s92, v152
	global_load_ushort v150, v[16:17], off offset:3072
	global_load_ushort v151, v[16:17], off offset:2560
	v_addc_co_u32_e32 v155, vcc, 0, v153, vcc
	global_load_ushort v152, v[154:155], off offset:3072
	global_load_ushort v153, v[154:155], off offset:2560
	s_lshl_b32 s90, s72, 1
	v_mov_b32_e32 v89, v189
	v_sub_u32_e32 v24, s53, v109
	v_add_u32_e32 v25, s52, v109
	v_cndmask_b32_e64 v26, v24, v25, s[42:43]
	v_mov_b64_e32 v[24:25], s[94:95]
	v_add_u32_e32 v28, s76, v26
	v_mad_i64_i32 v[26:27], s[40:41], v26, s63, v[24:25]
	v_lshl_add_u64 v[26:27], v[26:27], 0, s[90:91]
	v_lshl_add_u64 v[26:27], v[26:27], 0, v[88:89]
	v_mad_i64_i32 v[24:25], s[40:41], v28, s63, v[24:25]
	v_add_co_u32_e32 v26, vcc, s92, v26
	v_lshl_add_u64 v[24:25], v[24:25], 0, s[90:91]
	s_nop 0
	v_addc_co_u32_e32 v27, vcc, 0, v27, vcc
	v_lshl_add_u64 v[24:25], v[24:25], 0, v[88:89]
	s_nop 0
	v_add_co_u32_e32 v24, vcc, s92, v24
	s_nop 0
	s_nop 0
	v_addc_co_u32_e32 v25, vcc, 0, v25, vcc
	global_load_dwordx4 v[28:31], v[26:27], off offset:3584
	global_load_dwordx4 v[34:37], v[24:25], off offset:3584
	s_nop 0
	s_waitcnt vmcnt(0)
; #define LAS __attribute__((address_space(3)))
; template <bool OUT>
; __device__ __forceinline__ void gla_chunks(const Params& p, int l, const bf16_t* proj, LAS unsigned char* lds, int seg, int h, int dir, f32x4 (&Sacc)[4], float* outbuf, float& alog) {
;     ...
;           PART[tb * 64 + d] = run; }
;         { const int pr = tid >> 4, part = tid & 15; const int i0 = 2 * pr, ta = dir ? t0 + 63 - i0 : t0 + i0, tbb = dir ? ta - 1 : ta + 1;
;           const u32x4 a = *(const u32x4*)(proj + (size_t)ta * NP + GV + h * 128 + part * 8), b = *(const u32x4*)(proj + (size_t)tbb * NP + GV + h * 128 + part * 8);
; #pragma unroll
;           for (int e = 0; e < 4; ++e) {
;               *(LAS unsigned*)(VT + (part * 8 + 2 * e) * GP + i0) = (a[e] & 0xffffu) | (b[e] << 16);
;               *(LAS unsigned*)(VT + (part * 8 + 2 * e + 1) * GP + i0) = (a[e] >> 16) | (b[e] & 0xffff0000u); } }
;         __syncthreads();
;         { float off = 0.f, tot = 0.f;
; #pragma unroll
;           for (int q = 0; q < 8; ++q) { const float v = PART[q * 64 + d]; tot += v; if (q < tb) off += v; }
;           if (tb == 0) { EBL[d] = __expf(tot); alog += tot; }
	v_mov_b32_e32 v64, v156
	v_mov_b32_e32 v56, v157
	v_mov_b32_e32 v40, v158
	v_mov_b32_e32 v41, v159
	v_mov_b32_e32 v32, v160
	v_mov_b32_e32 v24, v161
	v_mov_b32_e32 v25, v162
	v_mov_b32_e32 v26, v163
	v_and_b32_e32 v16, 0xffff, v28
	v_lshrrev_b32_e32 v17, 16, v28
	v_lshl_or_b32 v16, v34, 16, v16
	v_and_or_b32 v17, v34, s0, v17
	v_add_u32_e32 v18, 0x6c00, v112
	ds_write2_b32 v18, v16, v17 offset1:36
	v_and_b32_e32 v16, 0xffff, v29
	v_lshrrev_b32_e32 v17, 16, v29
	v_lshl_or_b32 v16, v35, 16, v16
	v_and_or_b32 v17, v35, s0, v17
	ds_write2_b32 v18, v16, v17 offset0:72 offset1:108
	v_and_b32_e32 v16, 0xffff, v30
	v_lshrrev_b32_e32 v17, 16, v30
	v_lshl_or_b32 v16, v36, 16, v16
	v_and_or_b32 v17, v36, s0, v17
	ds_write2_b32 v18, v16, v17 offset0:144 offset1:180
	v_and_b32_e32 v16, 0xffff, v31
	v_lshrrev_b32_e32 v17, 16, v31
	v_lshl_or_b32 v16, v37, 16, v16
	v_and_or_b32 v17, v37, s0, v17
	ds_write_b32 v108, v26 offset:55552
	ds_write2_b32 v18, v16, v17 offset0:216 offset1:252
	s_waitcnt lgkmcnt(0)
	s_barrier
	ds_read2st64_b32 v[22:23], v110 offset0:217 offset1:218
	ds_read2st64_b32 v[20:21], v110 offset0:219 offset1:220
	ds_read2st64_b32 v[18:19], v110 offset0:221 offset1:222
	ds_read2st64_b32 v[16:17], v110 offset0:223 offset1:224
	s_andn2_b64 vcc, exec, s[80:81]
	s_waitcnt lgkmcnt(3)
	v_add_f32_e32 v28, 0, v22
	v_add_f32_e32 v22, v28, v23
	s_waitcnt lgkmcnt(2)
	v_add_f32_e32 v22, v22, v20
	v_add_f32_e32 v22, v22, v21
	s_waitcnt lgkmcnt(1)
	v_add_f32_e32 v22, v22, v18
	v_add_f32_e32 v22, v22, v19
	s_waitcnt lgkmcnt(0)
	v_add_f32_e32 v22, v22, v16
	v_add_f32_e32 v27, v22, v17
	s_cbranch_vccnz .LBB0_438
	v_mul_f32_e32 v22, 0x3fb8aa3b, v27
	v_exp_f32_e32 v22, v22
	ds_write_b32 v110, v22 offset:55296

; template <bool OUT>
; __device__ __forceinline__ void gla_chunks(const Params& p, int l, const bf16_t* proj, LAS unsigned char* lds, int seg, int h, int dir, f32x4 (&Sacc)[4], float* outbuf, float& alog) {
;     ...
;         { u32x4 L0[8], L1[8]; bf16_t kr[8], qr[8];
; #pragma unroll
;           for (int j = 0; j < 8; ++j) { const int i = tb * 8 + j, t = dir ? t0 + 63 - i : t0 + i;
;               const u32x4* lr = (const u32x4*)(proj + (size_t)t * NP + GLR + dir * 16); L0[j] = lr[0]; L1[j] = lr[1];
;               kr[j] = proj[(size_t)t * NP + GK + h * 64 + d]; qr[j] = OUT ? proj[(size_t)t * NP + GQ + h * 64 + d] : (bf16_t)0; }
.LBB0_488:
	s_and_b64 s[22:23], s[4:5], exec
	s_cselect_b32 s22, s34, s33
	s_lshl_b32 s48, s22, 6
	s_add_i32 s48, s48, s35
	s_or_b32 s22, s48, 63
	s_sub_i32 s23, s22, s36
	s_add_i32 s49, s48, s36
	s_and_b64 s[50:51], s[4:5], exec
	s_cselect_b32 s23, s49, s23
	s_mul_hi_i32 s49, s23, 0x3800
	s_mulk_i32 s23, 0x3800
	s_add_u32 s54, s94, s23
	s_addc_u32 s49, s95, s49
	s_add_u32 s50, s54, s47
	s_addc_u32 s51, s49, 0
	s_add_u32 s52, s50, 0x3600
	s_addc_u32 s53, s51, 0
	s_lshl_b32 s23, s28, 1
	global_load_dwordx4 v[72:75], v189, s[52:53] offset:16
	global_load_dwordx4 v[76:79], v210, s[50:51] offset:1536
	s_add_u32 s50, s54, s23
	s_addc_u32 s51, s49, 0
	s_sub_i32 s49, s22, s40
	s_add_i32 s52, s48, s40
	v_lshl_add_u64 v[16:17], s[50:51], 0, v[188:189]
	s_and_b64 s[50:51], s[4:5], exec
	s_cselect_b32 s49, s52, s49
	s_mul_hi_i32 s50, s49, 0x3800
	s_mulk_i32 s49, 0x3800
	s_add_u32 s49, s94, s49
	s_addc_u32 s54, s95, s50
	s_add_u32 s50, s49, s47
	s_addc_u32 s51, s54, 0
	v_add_co_u32_e32 v16, vcc, s92, v16
	s_add_u32 s52, s50, 0x3600
	s_nop 0
	v_addc_co_u32_e32 v17, vcc, 0, v17, vcc
	s_addc_u32 s53, s51, 0
	global_load_ushort v109, v[16:17], off offset:3072
	global_load_dwordx4 v[64:67], v189, s[52:53] offset:16
	global_load_dwordx4 v[68:71], v210, s[50:51] offset:1536
	s_add_u32 s50, s49, s23
	s_addc_u32 s51, s54, 0
	s_sub_i32 s49, s22, s41
	s_add_i32 s52, s48, s41
	v_lshl_add_u64 v[16:17], s[50:51], 0, v[188:189]
	s_and_b64 s[50:51], s[4:5], exec
	s_cselect_b32 s49, s52, s49
	s_mul_hi_i32 s50, s49, 0x3800
	s_mulk_i32 s49, 0x3800
	s_add_u32 s49, s94, s49
	s_addc_u32 s54, s95, s50
	s_add_u32 s50, s49, s47
	s_addc_u32 s51, s54, 0
	v_add_co_u32_e32 v16, vcc, s92, v16
	s_add_u32 s52, s50, 0x3600
	s_nop 0
	v_addc_co_u32_e32 v17, vcc, 0, v17, vcc
	s_addc_u32 s53, s51, 0
	global_load_ushort v110, v[16:17], off offset:3072
	global_load_dwordx4 v[56:59], v189, s[52:53] offset:16
	global_load_dwordx4 v[60:63], v210, s[50:51] offset:1536
	s_add_u32 s50, s49, s23
	s_addc_u32 s51, s54, 0
	s_sub_i32 s49, s22, s42
	s_add_i32 s52, s48, s42
	v_lshl_add_u64 v[16:17], s[50:51], 0, v[188:189]
	s_and_b64 s[50:51], s[4:5], exec
	s_cselect_b32 s49, s52, s49
	s_mul_hi_i32 s50, s49, 0x3800
	s_mulk_i32 s49, 0x3800
	s_add_u32 s49, s94, s49
	s_addc_u32 s54, s95, s50
	s_add_u32 s50, s49, s47
	s_addc_u32 s51, s54, 0
	v_add_co_u32_e32 v16, vcc, s92, v16
	s_add_u32 s52, s50, 0x3600
	s_nop 0
	v_addc_co_u32_e32 v17, vcc, 0, v17, vcc
	s_addc_u32 s53, s51, 0
	global_load_ushort v111, v[16:17], off offset:3072
	global_load_dwordx4 v[48:51], v189, s[52:53] offset:16
	global_load_dwordx4 v[52:55], v210, s[50:51] offset:1536
	s_add_u32 s50, s49, s23
	s_addc_u32 s51, s54, 0
	s_sub_i32 s49, s22, s43
	s_add_i32 s52, s48, s43
	v_lshl_add_u64 v[16:17], s[50:51], 0, v[188:189]
	s_and_b64 s[50:51], s[4:5], exec
	s_cselect_b32 s49, s52, s49
	s_mul_hi_i32 s50, s49, 0x3800
	s_mulk_i32 s49, 0x3800
	s_add_u32 s49, s94, s49
	s_addc_u32 s54, s95, s50
	s_add_u32 s50, s49, s47
	s_addc_u32 s51, s54, 0
	v_add_co_u32_e32 v16, vcc, s92, v16
	s_add_u32 s52, s50, 0x3600
	s_nop 0
	v_addc_co_u32_e32 v17, vcc, 0, v17, vcc
	s_addc_u32 s53, s51, 0
	global_load_ushort v112, v[16:17], off offset:3072
	global_load_dwordx4 v[40:43], v189, s[52:53] offset:16
	global_load_dwordx4 v[44:47], v210, s[50:51] offset:1536
	s_add_u32 s50, s49, s23
	s_addc_u32 s51, s54, 0
	s_sub_i32 s49, s22, s44
	s_add_i32 s52, s48, s44
	v_lshl_add_u64 v[16:17], s[50:51], 0, v[188:189]
	s_and_b64 s[50:51], s[4:5], exec
	s_cselect_b32 s49, s52, s49
	s_mul_hi_i32 s50, s49, 0x3800
	s_mulk_i32 s49, 0x3800
	s_add_u32 s49, s94, s49
	s_addc_u32 s54, s95, s50
	s_add_u32 s50, s49, s47
	s_addc_u32 s51, s54, 0
	v_add_co_u32_e32 v16, vcc, s92, v16
	s_add_u32 s52, s50, 0x3600
	s_nop 0
	v_addc_co_u32_e32 v17, vcc, 0, v17, vcc
	s_addc_u32 s53, s51, 0
	global_load_ushort v113, v[16:17], off offset:3072
	global_load_dwordx4 v[32:35], v189, s[52:53] offset:16
	global_load_dwordx4 v[36:39], v210, s[50:51] offset:1536
	s_add_u32 s50, s49, s23
	s_addc_u32 s51, s54, 0
	s_sub_i32 s49, s22, s45
	s_add_i32 s52, s48, s45
	v_lshl_add_u64 v[16:17], s[50:51], 0, v[188:189]
	s_and_b64 s[50:51], s[4:5], exec
	s_cselect_b32 s49, s52, s49
	s_mul_hi_i32 s50, s49, 0x3800
	s_mulk_i32 s49, 0x3800
	s_add_u32 s49, s94, s49
	s_addc_u32 s54, s95, s50
	s_add_u32 s50, s49, s47
	s_addc_u32 s51, s54, 0
	v_add_co_u32_e32 v16, vcc, s92, v16
	s_add_u32 s52, s50, 0x3600
	s_nop 0
	v_addc_co_u32_e32 v17, vcc, 0, v17, vcc
	s_addc_u32 s53, s51, 0
	global_load_ushort v114, v[16:17], off offset:3072
	global_load_dwordx4 v[24:27], v189, s[52:53] offset:16
	global_load_dwordx4 v[28:31], v210, s[50:51] offset:1536
	s_add_u32 s50, s49, s23
	s_addc_u32 s51, s54, 0
	s_sub_i32 s22, s22, s46
	s_add_i32 s49, s48, s46
	v_lshl_add_u64 v[16:17], s[50:51], 0, v[188:189]
	s_and_b64 s[50:51], s[4:5], exec
	s_cselect_b32 s22, s49, s22
	s_mul_hi_i32 s49, s22, 0x3800
	s_mulk_i32 s22, 0x3800
	s_add_u32 s22, s94, s22
	s_addc_u32 s49, s95, s49
	s_add_u32 s50, s22, s47
	s_addc_u32 s51, s49, 0
	s_add_u32 s52, s50, 0x3600
	s_addc_u32 s53, s51, 0
	s_add_u32 s22, s22, s23
	v_add_co_u32_e32 v16, vcc, s92, v16
	s_addc_u32 s23, s49, 0
	s_nop 0
	v_addc_co_u32_e32 v17, vcc, 0, v17, vcc
	v_lshl_add_u64 v[116:117], s[22:23], 0, v[188:189]
	v_add_co_u32_e32 v116, vcc, s92, v116
	global_load_ushort v115, v[16:17], off offset:3072
	s_nop 0
	v_addc_co_u32_e32 v117, vcc, 0, v117, vcc
	global_load_dwordx4 v[16:19], v189, s[52:53] offset:16
	global_load_dwordx4 v[20:23], v210, s[50:51] offset:1536
	s_nop 0
	global_load_ushort v116, v[116:117], off offset:3072
	s_waitcnt vmcnt(22)
; __device__ __forceinline__ float bf_lo(unsigned w) { return __uint_as_float(w << 16); }
; __device__ __forceinline__ float bf_hi(unsigned w) { return __uint_as_float(w & 0xffff0000u); }
; template <bool OUT>
; __device__ __forceinline__ void gla_chunks(const Params& p, int l, const bf16_t* proj, LAS unsigned char* lds, int seg, int h, int dir, f32x4 (&Sacc)[4], float* outbuf, float& alog) {
;     ...
;           for (int j = 0; j < 8; ++j) { const u32x4 l0 = L0[j], l1 = L1[j]; float z = bias;
; #pragma unroll
;               for (int e = 0; e < 4; ++e) { z += bf_lo(l0[e]) * w[e * 2] + bf_hi(l0[e]) * w[e * 2 + 1]; z += bf_lo(l1[e]) * w[8 + e * 2] + bf_hi(l1[e]) * w[8 + e * 2 + 1]; }
;               const float ls = fminf(z, 0.f) - __logf(1.0f + __expf(-fabsf(z)));
;               run += ls * (1.0f / 16.0f); bq[j] = run;
	v_lshlrev_b32_e32 v85, 16, v76
	v_and_b32_e32 v76, 0xffff0000, v76
	v_mul_f32_e32 v76, v87, v76
	v_fmac_f32_e32 v76, v95, v85
	v_lshlrev_b32_e32 v85, 16, v72
	v_and_b32_e32 v72, 0xffff0000, v72
	v_mul_f32_e32 v72, v92, v72
	v_add_f32_e32 v76, v86, v76
	v_fmac_f32_e32 v72, v91, v85
	v_add_f32_e32 v72, v72, v76
	v_lshlrev_b32_e32 v76, 16, v77
	v_and_b32_e32 v77, 0xffff0000, v77
	v_mul_f32_e32 v77, v89, v77
	v_fmac_f32_e32 v77, v88, v76
	v_lshlrev_b32_e32 v76, 16, v73
	v_and_b32_e32 v73, 0xffff0000, v73
	v_mul_f32_e32 v73, v94, v73
	v_add_f32_e32 v72, v77, v72
	v_fmac_f32_e32 v73, v93, v76
	v_and_b32_e32 v76, 0xffff0000, v78
	v_add_f32_e32 v72, v73, v72
	v_lshlrev_b32_e32 v73, 16, v78
	v_mul_f32_e32 v76, v96, v76
	v_fmac_f32_e32 v76, v90, v73
	v_lshlrev_b32_e32 v73, 16, v74
	v_and_b32_e32 v74, 0xffff0000, v74
	v_mul_f32_e32 v74, v100, v74
	v_add_f32_e32 v72, v76, v72
	v_fmac_f32_e32 v74, v99, v73
	v_add_f32_e32 v72, v74, v72
	v_and_b32_e32 v74, 0xffff0000, v79
	v_lshlrev_b32_e32 v73, 16, v79
	v_mul_f32_e32 v74, v98, v74
	v_fmac_f32_e32 v74, v97, v73
	v_add_f32_e32 v72, v74, v72
	v_lshlrev_b32_e32 v73, 16, v75
	v_and_b32_e32 v74, 0xffff0000, v75
	s_waitcnt vmcnt(19)
	v_lshlrev_b32_e32 v75, 16, v68
	v_and_b32_e32 v68, 0xffff0000, v68
	v_mul_f32_e32 v68, v87, v68
	v_fmac_f32_e32 v68, v95, v75
	v_lshlrev_b32_e32 v75, 16, v64
	v_and_b32_e32 v64, 0xffff0000, v64
	v_mul_f32_e32 v64, v92, v64
	v_add_f32_e32 v68, v86, v68
	v_fmac_f32_e32 v64, v91, v75
	v_add_f32_e32 v64, v64, v68
	v_lshlrev_b32_e32 v68, 16, v69
	v_and_b32_e32 v69, 0xffff0000, v69
	v_mul_f32_e32 v69, v89, v69
	v_fmac_f32_e32 v69, v88, v68
	v_lshlrev_b32_e32 v68, 16, v65
	v_and_b32_e32 v65, 0xffff0000, v65
	v_mul_f32_e32 v65, v94, v65
	v_add_f32_e32 v64, v69, v64
	v_fmac_f32_e32 v65, v93, v68
	v_and_b32_e32 v68, 0xffff0000, v70
	v_add_f32_e32 v64, v65, v64
	v_lshlrev_b32_e32 v65, 16, v70
	v_mul_f32_e32 v68, v96, v68
	v_mul_f32_e32 v74, v102, v74
	v_fmac_f32_e32 v68, v90, v65
	v_fmac_f32_e32 v74, v101, v73
	v_add_f32_e32 v64, v68, v64
	s_waitcnt vmcnt(16)
	v_lshlrev_b32_e32 v68, 16, v60
	v_and_b32_e32 v60, 0xffff0000, v60
	v_add_f32_e32 v72, v74, v72
	v_mul_f32_e32 v60, v87, v60
	v_mul_f32_e64 v73, |v72|, s60
	v_fmac_f32_e32 v60, v95, v68
	v_lshlrev_b32_e32 v68, 16, v56
	v_and_b32_e32 v56, 0xffff0000, v56
	v_exp_f32_e32 v73, v73
	v_lshlrev_b32_e32 v65, 16, v66
	v_and_b32_e32 v66, 0xffff0000, v66
	v_mul_f32_e32 v56, v92, v56
	v_mul_f32_e32 v66, v100, v66
	v_add_f32_e32 v60, v86, v60
	v_fmac_f32_e32 v56, v91, v68
	v_fmac_f32_e32 v66, v99, v65
	v_add_f32_e32 v56, v56, v60
	v_lshlrev_b32_e32 v60, 16, v61
	v_and_b32_e32 v61, 0xffff0000, v61
	v_add_f32_e32 v64, v66, v64
	v_and_b32_e32 v66, 0xffff0000, v71
	v_mul_f32_e32 v61, v89, v61
	v_add_f32_e32 v73, 1.0, v73
	v_lshlrev_b32_e32 v65, 16, v71
	v_mul_f32_e32 v66, v98, v66
	v_fmac_f32_e32 v61, v88, v60
	v_lshlrev_b32_e32 v60, 16, v57
	v_and_b32_e32 v57, 0xffff0000, v57
	v_cmp_gt_f32_e32 vcc, s1, v73
	v_fmac_f32_e32 v66, v97, v65
	v_mul_f32_e32 v57, v94, v57
	v_cndmask_b32_e64 v74, 0, 32, vcc
	v_add_f32_e32 v64, v66, v64
	v_and_b32_e32 v66, 0xffff0000, v67
	v_add_f32_e32 v56, v61, v56
	v_fmac_f32_e32 v57, v93, v60
	v_and_b32_e32 v60, 0xffff0000, v62
	v_ldexp_f32 v73, v73, v74
	v_lshlrev_b32_e32 v65, 16, v67
	v_mul_f32_e32 v66, v102, v66
	v_add_f32_e32 v56, v57, v56
	v_lshlrev_b32_e32 v57, 16, v62
	v_mul_f32_e32 v60, v96, v60
	v_log_f32_e32 v73, v73
	v_fmac_f32_e32 v66, v101, v65
	v_fmac_f32_e32 v60, v90, v57
	v_add_f32_e32 v65, v66, v64
	v_add_f32_e32 v56, v60, v56
	s_waitcnt vmcnt(13)
	v_lshlrev_b32_e32 v60, 16, v52
	v_and_b32_e32 v52, 0xffff0000, v52
	v_mul_f32_e64 v64, |v65|, s60
	v_mul_f32_e32 v52, v87, v52
	v_exp_f32_e32 v64, v64
	v_lshlrev_b32_e32 v57, 16, v58
	v_and_b32_e32 v58, 0xffff0000, v58
	v_fmac_f32_e32 v52, v95, v60
	v_lshlrev_b32_e32 v60, 16, v48
	v_and_b32_e32 v48, 0xffff0000, v48
	v_mul_f32_e32 v74, 0x3f317217, v73
	v_mul_f32_e32 v58, v100, v58
	v_mul_f32_e32 v48, v92, v48
	v_fma_f32 v74, v73, s74, -v74
	v_fmac_f32_e32 v58, v99, v57
	v_add_f32_e32 v52, v86, v52
	v_fmac_f32_e32 v48, v91, v60
	v_fmac_f32_e32 v74, 0x3377d1cf, v73
	v_add_f32_e32 v56, v58, v56
	v_and_b32_e32 v58, 0xffff0000, v63
	v_add_f32_e32 v48, v48, v52
	v_lshlrev_b32_e32 v52, 16, v53
	v_and_b32_e32 v53, 0xffff0000, v53
	v_fmac_f32_e32 v74, 0x3f317217, v73
	v_cmp_lt_f32_e64 s[22:23], |v73|, s70
	v_add_f32_e32 v64, 1.0, v64
	v_lshlrev_b32_e32 v57, 16, v63
	v_mul_f32_e32 v58, v98, v58
	v_mul_f32_e32 v53, v89, v53
	v_cndmask_b32_e64 v66, v73, v74, s[22:23]
	v_cndmask_b32_e32 v67, 0, v214, vcc
	v_cmp_gt_f32_e32 vcc, s1, v64
	v_fmac_f32_e32 v58, v97, v57
	v_fmac_f32_e32 v53, v88, v52
	v_lshlrev_b32_e32 v52, 16, v49
	v_and_b32_e32 v49, 0xffff0000, v49
	v_sub_f32_e32 v66, v66, v67
	v_cndmask_b32_e64 v67, 0, 32, vcc
	v_add_f32_e32 v56, v58, v56
	v_and_b32_e32 v58, 0xffff0000, v59
	v_mul_f32_e32 v49, v94, v49
	v_ldexp_f32 v64, v64, v67
	v_lshlrev_b32_e32 v57, 16, v59
	v_mul_f32_e32 v58, v102, v58
	v_add_f32_e32 v48, v53, v48
	v_fmac_f32_e32 v49, v93, v52
	v_and_b32_e32 v52, 0xffff0000, v54
	v_log_f32_e32 v67, v64
	v_fmac_f32_e32 v58, v101, v57
	v_add_f32_e32 v48, v49, v48
	v_lshlrev_b32_e32 v49, 16, v54
	v_mul_f32_e32 v52, v96, v52
	v_add_f32_e32 v57, v58, v56
	v_fmac_f32_e32 v52, v90, v49
	v_mul_f32_e64 v56, |v57|, s60
	v_add_f32_e32 v48, v52, v48
	s_waitcnt vmcnt(10)
; __device__ __forceinline__ float bf_lo(unsigned w) { return __uint_as_float(w << 16); }
; __device__ __forceinline__ float bf_hi(unsigned w) { return __uint_as_float(w & 0xffff0000u); }
; template <bool OUT>
; __device__ __forceinline__ void gla_chunks(const Params& p, int l, const bf16_t* proj, LAS unsigned char* lds, int seg, int h, int dir, f32x4 (&Sacc)[4], float* outbuf, float& alog) {
;     ...
;           for (int j = 0; j < 8; ++j) { const u32x4 l0 = L0[j], l1 = L1[j]; float z = bias;
; #pragma unroll
;               for (int e = 0; e < 4; ++e) { z += bf_lo(l0[e]) * w[e * 2] + bf_hi(l0[e]) * w[e * 2 + 1]; z += bf_lo(l1[e]) * w[8 + e * 2] + bf_hi(l1[e]) * w[8 + e * 2 + 1]; }
;               const float ls = fminf(z, 0.f) - __logf(1.0f + __expf(-fabsf(z)));
;               run += ls * (1.0f / 16.0f); bq[j] = run;
	v_lshlrev_b32_e32 v52, 16, v44
	v_and_b32_e32 v44, 0xffff0000, v44
	v_min_f32_e32 v72, 0, v72
	v_exp_f32_e32 v56, v56
	v_lshlrev_b32_e32 v49, 16, v50
	v_and_b32_e32 v50, 0xffff0000, v50
	v_mul_f32_e32 v44, v87, v44
	v_sub_f32_e32 v64, v72, v66
	v_mul_f32_e32 v66, 0x3f317217, v67
	v_mul_f32_e32 v50, v100, v50
	v_fmac_f32_e32 v44, v95, v52
	v_lshlrev_b32_e32 v52, 16, v40
	v_and_b32_e32 v40, 0xffff0000, v40
	v_fma_f32 v66, v67, s74, -v66
	v_fmac_f32_e32 v50, v99, v49
	v_mul_f32_e32 v40, v92, v40
	v_fmac_f32_e32 v66, 0x3377d1cf, v67
	v_add_f32_e32 v48, v50, v48
	v_and_b32_e32 v50, 0xffff0000, v55
	v_add_f32_e32 v44, v86, v44
	v_fmac_f32_e32 v40, v91, v52
	v_fmac_f32_e32 v66, 0x3f317217, v67
	v_cmp_lt_f32_e64 s[22:23], |v67|, s70
	v_add_f32_e32 v56, 1.0, v56
	v_lshlrev_b32_e32 v49, 16, v55
	v_mul_f32_e32 v50, v98, v50
	v_add_f32_e32 v40, v40, v44
	v_lshlrev_b32_e32 v44, 16, v45
	v_and_b32_e32 v45, 0xffff0000, v45
	v_cndmask_b32_e64 v58, v67, v66, s[22:23]
	v_cndmask_b32_e32 v59, 0, v214, vcc
	v_cmp_gt_f32_e32 vcc, s1, v56
	v_fmac_f32_e32 v50, v97, v49
	v_mul_f32_e32 v45, v89, v45
	v_sub_f32_e32 v58, v58, v59
	v_cndmask_b32_e64 v59, 0, 32, vcc
	v_add_f32_e32 v48, v50, v48
	v_and_b32_e32 v50, 0xffff0000, v51
	v_fmac_f32_e32 v45, v88, v44
	v_lshlrev_b32_e32 v44, 16, v41
	v_and_b32_e32 v41, 0xffff0000, v41
	v_ldexp_f32 v56, v56, v59
	v_lshlrev_b32_e32 v49, 16, v51
	v_mul_f32_e32 v50, v102, v50
	v_mul_f32_e32 v41, v94, v41
	v_log_f32_e32 v59, v56
	v_fmac_f32_e32 v50, v101, v49
	v_add_f32_e32 v40, v45, v40
	v_fmac_f32_e32 v41, v93, v44
	v_and_b32_e32 v44, 0xffff0000, v46
	v_add_f32_e32 v49, v50, v48
	v_add_f32_e32 v40, v41, v40
	v_lshlrev_b32_e32 v41, 16, v46
	v_mul_f32_e32 v44, v96, v44
	v_mul_f32_e64 v48, |v49|, s60
	v_fmac_f32_e32 v44, v90, v41
	v_min_f32_e32 v65, 0, v65
	v_exp_f32_e32 v48, v48
	v_add_f32_e32 v40, v44, v40
	v_lshlrev_b32_e32 v41, 16, v42
	v_and_b32_e32 v42, 0xffff0000, v42
	s_waitcnt vmcnt(7)
	v_lshlrev_b32_e32 v44, 16, v36
	v_and_b32_e32 v36, 0xffff0000, v36
	v_sub_f32_e32 v56, v65, v58
	v_mul_f32_e32 v58, 0x3f317217, v59
	v_mul_f32_e32 v42, v100, v42
	v_mul_f32_e32 v36, v87, v36
	v_fma_f32 v58, v59, s74, -v58
	v_fmac_f32_e32 v42, v99, v41
	v_fmac_f32_e32 v36, v95, v44
	v_lshlrev_b32_e32 v44, 16, v32
	v_and_b32_e32 v32, 0xffff0000, v32
	v_fmac_f32_e32 v58, 0x3377d1cf, v59
	v_add_f32_e32 v40, v42, v40
	v_and_b32_e32 v42, 0xffff0000, v47
	v_mul_f32_e32 v32, v92, v32
	v_fmac_f32_e32 v58, 0x3f317217, v59
	v_cmp_lt_f32_e64 s[22:23], |v59|, s70
	v_add_f32_e32 v48, 1.0, v48
	v_lshlrev_b32_e32 v41, 16, v47
	v_mul_f32_e32 v42, v98, v42
	v_add_f32_e32 v36, v86, v36
	v_fmac_f32_e32 v32, v91, v44
	v_cndmask_b32_e64 v50, v59, v58, s[22:23]
	v_cndmask_b32_e32 v51, 0, v214, vcc
	v_cmp_gt_f32_e32 vcc, s1, v48
	v_fmac_f32_e32 v42, v97, v41
	v_add_f32_e32 v32, v32, v36
	v_lshlrev_b32_e32 v36, 16, v37
	v_and_b32_e32 v37, 0xffff0000, v37
	v_sub_f32_e32 v50, v50, v51
	v_cndmask_b32_e64 v51, 0, 32, vcc
	v_add_f32_e32 v40, v42, v40
	v_and_b32_e32 v42, 0xffff0000, v43
	v_mul_f32_e32 v37, v89, v37
	v_ldexp_f32 v48, v48, v51
	v_lshlrev_b32_e32 v41, 16, v43
	v_mul_f32_e32 v42, v102, v42
	v_fmac_f32_e32 v37, v88, v36
	v_lshlrev_b32_e32 v36, 16, v33
	v_and_b32_e32 v33, 0xffff0000, v33
	v_log_f32_e32 v51, v48
	v_fmac_f32_e32 v42, v101, v41
	v_mul_f32_e32 v33, v94, v33
	v_add_f32_e32 v41, v42, v40
	v_add_f32_e32 v32, v37, v32
	v_fmac_f32_e32 v33, v93, v36
	v_and_b32_e32 v36, 0xffff0000, v38
	v_mul_f32_e64 v40, |v41|, s60
	v_add_f32_e32 v32, v33, v32
	v_lshlrev_b32_e32 v33, 16, v38
	v_mul_f32_e32 v36, v96, v36
	v_min_f32_e32 v57, 0, v57
	v_exp_f32_e32 v40, v40
	v_fmac_f32_e32 v36, v90, v33
	v_lshlrev_b32_e32 v33, 16, v34
	v_and_b32_e32 v34, 0xffff0000, v34
	v_sub_f32_e32 v48, v57, v50
	v_mul_f32_e32 v50, 0x3f317217, v51
	v_mul_f32_e32 v34, v100, v34
	v_fma_f32 v50, v51, s74, -v50
	v_add_f32_e32 v32, v36, v32
	v_fmac_f32_e32 v34, v99, v33
	v_fmac_f32_e32 v50, 0x3377d1cf, v51
	v_add_f32_e32 v32, v34, v32
	v_and_b32_e32 v34, 0xffff0000, v39
	v_fmac_f32_e32 v50, 0x3f317217, v51
	v_cmp_lt_f32_e64 s[22:23], |v51|, s70
	v_add_f32_e32 v40, 1.0, v40
	v_lshlrev_b32_e32 v33, 16, v39
	v_mul_f32_e32 v34, v98, v34
	v_cndmask_b32_e64 v42, v51, v50, s[22:23]
	v_cndmask_b32_e32 v43, 0, v214, vcc
	v_cmp_gt_f32_e32 vcc, s1, v40
	v_fmac_f32_e32 v34, v97, v33
	v_sub_f32_e32 v42, v42, v43
	v_cndmask_b32_e64 v43, 0, 32, vcc
	v_add_f32_e32 v32, v34, v32
	v_and_b32_e32 v34, 0xffff0000, v35
	v_ldexp_f32 v40, v40, v43
	v_lshlrev_b32_e32 v33, 16, v35
	v_mul_f32_e32 v34, v102, v34
	v_log_f32_e32 v43, v40
	v_fmac_f32_e32 v34, v101, v33
	v_add_f32_e32 v33, v34, v32
	v_mul_f32_e64 v32, |v33|, s60
	v_min_f32_e32 v49, 0, v49
	v_exp_f32_e32 v32, v32
	v_sub_f32_e32 v40, v49, v42
	v_mul_f32_e32 v42, 0x3f317217, v43
	v_fma_f32 v42, v43, s74, -v42
	v_fmac_f32_e32 v42, 0x3377d1cf, v43
	v_fmac_f32_e32 v42, 0x3f317217, v43
	v_cmp_lt_f32_e64 s[22:23], |v43|, s70
	v_add_f32_e32 v32, 1.0, v32
	v_cndmask_b32_e32 v35, 0, v214, vcc
	v_cndmask_b32_e64 v34, v43, v42, s[22:23]
	v_cmp_gt_f32_e32 vcc, s1, v32
	v_sub_f32_e32 v34, v34, v35
	v_min_f32_e32 v41, 0, v41
	v_cndmask_b32_e64 v35, 0, 32, vcc
	v_ldexp_f32 v32, v32, v35
	v_log_f32_e32 v35, v32
	v_sub_f32_e32 v32, v41, v34
	v_mov_b32_e32 v85, v189
	v_cndmask_b32_e32 v39, 0, v214, vcc
	v_mul_f32_e32 v34, 0x3f317217, v35
	v_fma_f32 v34, v35, s74, -v34
	v_fmac_f32_e32 v34, 0x3377d1cf, v35
	v_fmac_f32_e32 v34, 0x3f317217, v35
	v_cmp_lt_f32_e64 s[22:23], |v35|, s70
	v_min_f32_e32 v33, 0, v33
	v_fma_f32 v64, v64, s75, 0
	v_cndmask_b32_e64 v38, v35, v34, s[22:23]
	s_waitcnt vmcnt(4)
; #define LAS __attribute__((address_space(3)))
; __device__ __forceinline__ float bf_lo(unsigned w) { return __uint_as_float(w << 16); }
; __device__ __forceinline__ float bf_hi(unsigned w) { return __uint_as_float(w & 0xffff0000u); }
; __device__ __forceinline__ float bf2f(bf16_t b) { return __uint_as_float(((unsigned)b) << 16); }
; template <bool OUT>
; __device__ __forceinline__ void gla_chunks(const Params& p, int l, const bf16_t* proj, LAS unsigned char* lds, int seg, int h, int dir, f32x4 (&Sacc)[4], float* outbuf, float& alog) {
;     ...
;           for (int j = 0; j < 8; ++j) { const u32x4 l0 = L0[j], l1 = L1[j]; float z = bias;
; #pragma unroll
;               for (int e = 0; e < 4; ++e) { z += bf_lo(l0[e]) * w[e * 2] + bf_hi(l0[e]) * w[e * 2 + 1]; z += bf_lo(l1[e]) * w[8 + e * 2] + bf_hi(l1[e]) * w[8 + e * 2 + 1]; }
;               const float ls = fminf(z, 0.f) - __logf(1.0f + __expf(-fabsf(z)));
;               run += ls * (1.0f / 16.0f); bq[j] = run;
;               kv[j] = bf2f(kr[j]);
;               if (OUT) qv[j] = bf2f(qr[j]) * 0.125f; }
;           PART[tb * 64 + d] = run; }
;         { const int pr = tid >> 4, part = tid & 15; const int i0 = 2 * pr, ta = dir ? t0 + 63 - i0 : t0 + i0, tbb = dir ? ta - 1 : ta + 1;
;           const u32x4 a = *(const u32x4*)(proj + (size_t)ta * NP + GV + h * 128 + part * 8), b = *(const u32x4*)(proj + (size_t)tbb * NP + GV + h * 128 + part * 8);
; #pragma unroll
;           for (int e = 0; e < 4; ++e) {
;               *(LAS unsigned*)(VT + (part * 8 + 2 * e) * GP + i0) = (a[e] & 0xffffu) | (b[e] << 16);
;               *(LAS unsigned*)(VT + (part * 8 + 2 * e + 1) * GP + i0) = (a[e] >> 16) | (b[e] & 0xffff0000u); } }
	v_lshlrev_b32_e32 v34, 16, v28
	v_and_b32_e32 v28, 0xffff0000, v28
	v_mul_f32_e32 v28, v87, v28
	v_fmac_f32_e32 v28, v95, v34
	v_lshlrev_b32_e32 v34, 16, v24
	v_and_b32_e32 v24, 0xffff0000, v24
	v_mul_f32_e32 v24, v92, v24
	v_add_f32_e32 v28, v86, v28
	v_fmac_f32_e32 v24, v91, v34
	v_add_f32_e32 v24, v24, v28
	v_lshlrev_b32_e32 v28, 16, v29
	v_and_b32_e32 v29, 0xffff0000, v29
	v_mul_f32_e32 v29, v89, v29
	v_fmac_f32_e32 v29, v88, v28
	v_lshlrev_b32_e32 v28, 16, v25
	v_and_b32_e32 v25, 0xffff0000, v25
	v_mul_f32_e32 v25, v94, v25
	v_add_f32_e32 v24, v29, v24
	v_fmac_f32_e32 v25, v93, v28
	v_and_b32_e32 v28, 0xffff0000, v30
	v_add_f32_e32 v24, v25, v24
	v_lshlrev_b32_e32 v25, 16, v30
	v_mul_f32_e32 v28, v96, v28
	v_fmac_f32_e32 v28, v90, v25
	v_lshlrev_b32_e32 v25, 16, v26
	v_and_b32_e32 v26, 0xffff0000, v26
	v_mul_f32_e32 v26, v100, v26
	v_add_f32_e32 v24, v28, v24
	v_fmac_f32_e32 v26, v99, v25
	v_add_f32_e32 v24, v26, v24
	v_and_b32_e32 v26, 0xffff0000, v31
	v_lshlrev_b32_e32 v25, 16, v31
	v_mul_f32_e32 v26, v98, v26
	v_fmac_f32_e32 v26, v97, v25
	v_add_f32_e32 v24, v26, v24
	v_and_b32_e32 v26, 0xffff0000, v27
	v_lshlrev_b32_e32 v25, 16, v27
	v_mul_f32_e32 v26, v102, v26
	v_fmac_f32_e32 v26, v101, v25
	v_add_f32_e32 v41, v26, v24
	v_mul_f32_e64 v24, |v41|, s60
	v_exp_f32_e32 v42, v24
	v_sub_u32_e32 v24, s48, v104
	v_add_u32_e32 v24, 63, v24
	v_add_u32_e32 v25, s48, v104
	v_cndmask_b32_e64 v26, v24, v25, s[4:5]
	v_mov_b64_e32 v[24:25], s[94:95]
	v_add_u32_e32 v28, s37, v26
	v_mad_i64_i32 v[26:27], s[22:23], v26, s63, v[24:25]
	v_lshl_add_u64 v[26:27], v[26:27], 0, s[90:91]
	v_lshl_add_u64 v[26:27], v[26:27], 0, v[84:85]
	v_mad_i64_i32 v[24:25], s[22:23], v28, s63, v[24:25]
	v_add_co_u32_e32 v26, vcc, s92, v26
	v_lshl_add_u64 v[24:25], v[24:25], 0, s[90:91]
	s_nop 0
	v_addc_co_u32_e32 v27, vcc, 0, v27, vcc
	v_lshl_add_u64 v[24:25], v[24:25], 0, v[84:85]
	v_add_co_u32_e32 v24, vcc, s92, v24
	v_fmamk_f32 v56, v56, 0x3d800000, v64
	s_nop 0
	v_addc_co_u32_e32 v25, vcc, 0, v25, vcc
	global_load_dwordx4 v[28:31], v[26:27], off offset:3584
	global_load_dwordx4 v[34:37], v[24:25], off offset:3584
	v_sub_f32_e32 v24, v38, v39
	v_sub_f32_e32 v24, v33, v24
	s_waitcnt vmcnt(3)
	v_lshlrev_b32_e32 v33, 16, v20
	v_and_b32_e32 v20, 0xffff0000, v20
	v_mul_f32_e32 v20, v87, v20
	v_fmac_f32_e32 v20, v95, v33
	v_lshlrev_b32_e32 v33, 16, v16
	v_and_b32_e32 v16, 0xffff0000, v16
	v_mul_f32_e32 v16, v92, v16
	v_add_f32_e32 v20, v86, v20
	v_fmac_f32_e32 v16, v91, v33
	v_add_f32_e32 v16, v16, v20
	v_lshlrev_b32_e32 v20, 16, v21
	v_and_b32_e32 v21, 0xffff0000, v21
	v_mul_f32_e32 v21, v89, v21
	v_fmac_f32_e32 v21, v88, v20
	v_lshlrev_b32_e32 v20, 16, v17
	v_and_b32_e32 v17, 0xffff0000, v17
	v_mul_f32_e32 v17, v94, v17
	v_add_f32_e32 v16, v21, v16
	v_fmac_f32_e32 v17, v93, v20
	v_and_b32_e32 v20, 0xffff0000, v22
	v_add_f32_e32 v16, v17, v16
	v_lshlrev_b32_e32 v17, 16, v22
	v_mul_f32_e32 v20, v96, v20
	v_fmac_f32_e32 v20, v90, v17
	v_lshlrev_b32_e32 v17, 16, v18
	v_and_b32_e32 v18, 0xffff0000, v18
	v_mul_f32_e32 v18, v100, v18
	v_add_f32_e32 v16, v20, v16
	v_fmac_f32_e32 v18, v99, v17
	v_add_f32_e32 v16, v18, v16
	v_and_b32_e32 v18, 0xffff0000, v23
	v_add_f32_e32 v25, 1.0, v42
	v_lshlrev_b32_e32 v17, 16, v23
	v_mul_f32_e32 v18, v98, v18
	v_cmp_gt_f32_e32 vcc, s1, v25
	v_fmac_f32_e32 v18, v97, v17
	v_add_f32_e32 v16, v18, v16
	v_cndmask_b32_e64 v26, 0, 32, vcc
	v_and_b32_e32 v18, 0xffff0000, v19
	v_ldexp_f32 v25, v25, v26
	v_lshlrev_b32_e32 v17, 16, v19
	v_mul_f32_e32 v18, v102, v18
	v_log_f32_e32 v25, v25
	v_fmac_f32_e32 v18, v101, v17
	v_add_f32_e32 v16, v18, v16
	v_mul_f32_e64 v17, |v16|, s60
	v_exp_f32_e32 v17, v17
	v_mul_f32_e32 v27, 0x3f317217, v25
	v_fma_f32 v27, v25, s74, -v27
	v_fmac_f32_e32 v27, 0x3377d1cf, v25
	v_fmac_f32_e32 v27, 0x3f317217, v25
	v_cmp_lt_f32_e64 s[22:23], |v25|, s70
	v_add_f32_e32 v17, 1.0, v17
	v_cndmask_b32_e32 v19, 0, v214, vcc
	v_cndmask_b32_e64 v18, v25, v27, s[22:23]
	v_cmp_gt_f32_e32 vcc, s1, v17
	v_sub_f32_e32 v18, v18, v19
	v_fmamk_f32 v48, v48, 0x3d800000, v56
	v_cndmask_b32_e64 v19, 0, 32, vcc
	v_ldexp_f32 v17, v17, v19
	v_log_f32_e32 v17, v17
	v_fmamk_f32 v40, v40, 0x3d800000, v48
	v_fmamk_f32 v32, v32, 0x3d800000, v40
	v_min_f32_e32 v26, 0, v41
	v_fmamk_f32 v24, v24, 0x3d800000, v32
	v_sub_f32_e32 v18, v26, v18
	v_fmamk_f32 v25, v18, 0x3d800000, v24
	v_mul_f32_e32 v18, 0x3f317217, v17
	v_fma_f32 v18, v17, s74, -v18
	v_fmac_f32_e32 v18, 0x3377d1cf, v17
	v_fmac_f32_e32 v18, 0x3f317217, v17
	v_cmp_lt_f32_e64 s[22:23], |v17|, s70
	v_min_f32_e32 v16, 0, v16
	s_nop 0
	v_cndmask_b32_e64 v17, v17, v18, s[22:23]
	v_cndmask_b32_e32 v18, 0, v214, vcc
	v_sub_f32_e32 v17, v17, v18
	v_sub_f32_e32 v16, v16, v17
	v_fmamk_f32 v26, v16, 0x3d800000, v25
	s_waitcnt vmcnt(1)
	v_and_b32_e32 v16, 0xffff, v28
	v_lshrrev_b32_e32 v17, 16, v28
	s_waitcnt vmcnt(0)
	s_sub_i32 s54, s48, s36
	s_add_i32 s54, s54, 63
	s_add_i32 s52, s48, s36
	s_and_b64 s[22:23], s[4:5], exec
	s_cselect_b32 s54, s52, s54
	s_cselect_b32 s53, 1, -1
	s_lshl_b32 s53, s53, 11
	s_lshl_b32 s54, s54, 11
	s_lshl_b32 s52, s47, 5
	s_add_i32 s54, s54, s52
	s_lshl_b32 s52, s28, 2
	s_add_i32 s54, s54, s52
	v_mov_b32_e32 v182, s53
	v_add_u32_e32 v180, s54, v105
	s_add_u32 s52, s94, 0x11000000
	s_addc_u32 s53, s95, 0
	global_store_dword v180, v64, s[52:53]
	v_add_u32_e32 v181, v180, v182
	global_store_dword v181, v56, s[52:53]
	v_add_u32_e32 v180, v181, v182
	global_store_dword v180, v48, s[52:53]
	v_add_u32_e32 v181, v180, v182
	global_store_dword v181, v40, s[52:53]
	v_add_u32_e32 v180, v181, v182
	global_store_dword v180, v32, s[52:53]
	v_add_u32_e32 v181, v180, v182
	global_store_dword v181, v24, s[52:53]
	v_add_u32_e32 v180, v181, v182
	global_store_dword v180, v25, s[52:53]
	v_add_u32_e32 v181, v180, v182
	global_store_dword v181, v26, s[52:53]
	v_lshl_or_b32 v16, v34, 16, v16
	v_and_or_b32 v17, v34, s0, v17
	v_add_u32_e32 v18, 0x6c00, v106
	ds_write2_b32 v18, v16, v17 offset1:36
	v_and_b32_e32 v16, 0xffff, v29
	v_lshrrev_b32_e32 v17, 16, v29
	v_lshl_or_b32 v16, v35, 16, v16
	v_and_or_b32 v17, v35, s0, v17
	ds_write2_b32 v18, v16, v17 offset0:72 offset1:108
	v_and_b32_e32 v16, 0xffff, v30
	v_lshrrev_b32_e32 v17, 16, v30
	v_lshl_or_b32 v16, v36, 16, v16
	v_and_or_b32 v17, v36, s0, v17
	ds_write2_b32 v18, v16, v17 offset0:144 offset1:180
	v_and_b32_e32 v16, 0xffff, v31
	v_lshrrev_b32_e32 v17, 16, v31
	v_lshl_or_b32 v16, v37, 16, v16
	v_and_or_b32 v17, v37, s0, v17
	ds_write_b32 v103, v26 offset:55552
	ds_write2_b32 v18, v16, v17 offset0:216 offset1:252
	s_waitcnt lgkmcnt(0)
	s_barrier
; template <bool OUT>
; __device__ __forceinline__ void gla_chunks(const Params& p, int l, const bf16_t* proj, LAS unsigned char* lds, int seg, int h, int dir, f32x4 (&Sacc)[4], float* outbuf, float& alog) {
;     ...
;         { float off = 0.f, tot = 0.f;
; #pragma unroll
;           for (int q = 0; q < 8; ++q) { const float v = PART[q * 64 + d]; tot += v; if (q < tb) off += v; }
;           if (tb == 0) { EBL[d] = __expf(tot); alog += tot; }
	ds_read2st64_b32 v[22:23], v105 offset0:217 offset1:218
	ds_read2st64_b32 v[20:21], v105 offset0:219 offset1:220
	ds_read2st64_b32 v[18:19], v105 offset0:221 offset1:222
	ds_read2st64_b32 v[16:17], v105 offset0:223 offset1:224
	s_andn2_b64 vcc, exec, s[24:25]
	s_waitcnt lgkmcnt(3)
	v_add_f32_e32 v27, 0, v22
	v_add_f32_e32 v22, v27, v23
	s_waitcnt lgkmcnt(2)
	v_add_f32_e32 v22, v22, v20
	v_add_f32_e32 v22, v22, v21
	s_waitcnt lgkmcnt(1)
	v_add_f32_e32 v22, v22, v18
	v_add_f32_e32 v22, v22, v19
	s_waitcnt lgkmcnt(0)
	v_add_f32_e32 v22, v22, v16
	v_add_f32_e32 v22, v22, v17
	s_cbranch_vccnz .LBB0_487
	v_mul_f32_e32 v28, 0x3fb8aa3b, v22
	v_exp_f32_e32 v28, v28
	v_add_f32_e32 v83, v83, v22
	ds_write_b32 v105, v28 offset:55296
	s_branch .LBB0_487
